# copy-out back on WGs 0-63+224-255, sample pool W=8 window loads batched, G1 start stagger
# speedup vs baseline: 1.0322x; 1.0025x over previous
.LBB0_149:
	s_bfe_u32 s98, s2, 0x20003
	s_cmp_eq_u32 s98, 0
	s_cbranch_scc1 .Lstag_done
.Lstag_loop:
	s_sleep 10
	s_sub_u32 s98, s98, 1
	s_cmp_lg_u32 s98, 0
	s_cbranch_scc1 .Lstag_loop

.LBB0_291:
	s_andn2_b64 vcc, exec, s[16:17]
	s_cbranch_vccnz .LBB0_293
	s_lshr_b32 s16, s40, 3
	v_add_u32_e32 v226, s16, v170
	v_readlane_b32 s48, v252, 4
	v_readlane_b32 s49, v252, 5
	v_lshlrev_b32_e32 v160, 1, v171
	v_lshlrev_b32_e32 v227, 3, v226
	v_add_u32_e32 v226, s6, v226
	v_mul_u32_u24_e32 v226, 0xf000, v226
	v_lshl_add_u32 v226, v171, 2, v226
	v_add_u32_e32 v229, 0x8000000, v160
	v_lshl_add_u32 v227, v227, 13, v229
	v_add_u32_e32 v212, 0x8000, v226
	global_load_dwordx4 v[64:67], v212, s[48:49] offset:2048
	global_load_dwordx4 v[68:71], v212, s[48:49] offset:2064
	v_add_u32_e32 v213, 0x9000, v226
	global_load_dwordx4 v[72:75], v213, s[48:49] offset:2048
	global_load_dwordx4 v[76:79], v213, s[48:49] offset:2064
	v_add_u32_e32 v214, 0xa000, v226
	global_load_dwordx4 v[80:83], v214, s[48:49] offset:2048
	global_load_dwordx4 v[84:87], v214, s[48:49] offset:2064
	v_add_u32_e32 v215, 0xb000, v226
	global_load_dwordx4 v[88:91], v215, s[48:49] offset:2048
	global_load_dwordx4 v[92:95], v215, s[48:49] offset:2064
	v_add_u32_e32 v212, 0xc000, v226
	global_load_dwordx4 v[96:99], v212, s[48:49] offset:2048
	global_load_dwordx4 v[100:103], v212, s[48:49] offset:2064
	v_add_u32_e32 v213, 0xd000, v226
	global_load_dwordx4 v[104:107], v213, s[48:49] offset:2048
	global_load_dwordx4 v[108:111], v213, s[48:49] offset:2064
	v_add_u32_e32 v214, 0xe000, v226
	global_load_dwordx4 v[112:115], v214, s[48:49] offset:2048
	global_load_dwordx4 v[116:119], v214, s[48:49] offset:2064
	global_load_dwordx4 v[172:175], v227, s[0:1] offset:1024
	v_add_u32_e32 v213, 0x2000, v227
	global_load_dwordx4 v[176:179], v213, s[0:1] offset:1024
	v_add_u32_e32 v214, 0x4000, v227
	global_load_dwordx4 v[180:183], v214, s[0:1] offset:1024
	v_add_u32_e32 v215, 0x6000, v227
	global_load_dwordx4 v[184:187], v215, s[0:1] offset:1024
	v_add_u32_e32 v212, 0x8000, v227
	global_load_dwordx4 v[188:191], v212, s[0:1] offset:1024
	v_add_u32_e32 v213, 0xa000, v227
	global_load_dwordx4 v[192:195], v213, s[0:1] offset:1024
	v_add_u32_e32 v214, 0xc000, v227
	global_load_dwordx4 v[196:199], v214, s[0:1] offset:1024
	v_add_u32_e32 v215, 0xe000, v227
	global_load_dwordx4 v[200:203], v215, s[0:1] offset:1024
	s_mov_b32 s44, 0xffff0000
	s_mov_b32 s45, 0x3e000000
	v_mul_u32_u24_e32 v229, 0x1080, v170
	v_add_u32_e32 v160, v229, v160
	v_mov_b64_e32 v[204:205], 0
	v_mov_b64_e32 v[206:207], 0
	v_mov_b64_e32 v[208:209], 0
	v_mov_b64_e32 v[210:211], 0
	s_waitcnt vmcnt(20)
	v_cvt_pk_bf16_f32 v64, v64, v65
	v_cvt_pk_bf16_f32 v65, v66, v67
	v_cvt_pk_bf16_f32 v66, v68, v69
	v_cvt_pk_bf16_f32 v67, v70, v71
	v_lshlrev_b32_e32 v212, 16, v64
	v_and_b32_e32 v213, s44, v64
	v_lshlrev_b32_e32 v214, 16, v65
	v_and_b32_e32 v215, s44, v65
	v_lshlrev_b32_e32 v216, 16, v66
	v_and_b32_e32 v217, s44, v66
	v_lshlrev_b32_e32 v222, 16, v67
	v_and_b32_e32 v223, s44, v67
	v_pk_add_f32 v[204:205], v[204:205], v[212:213]
	v_pk_add_f32 v[206:207], v[206:207], v[214:215]
	v_pk_add_f32 v[208:209], v[208:209], v[216:217]
	v_pk_add_f32 v[210:211], v[210:211], v[222:223]
	s_waitcnt vmcnt(18)
	v_cvt_pk_bf16_f32 v72, v72, v73
	v_cvt_pk_bf16_f32 v73, v74, v75
	v_cvt_pk_bf16_f32 v74, v76, v77
	v_cvt_pk_bf16_f32 v75, v78, v79
	v_lshlrev_b32_e32 v212, 16, v72
	v_and_b32_e32 v213, s44, v72
	v_lshlrev_b32_e32 v214, 16, v73
	v_and_b32_e32 v215, s44, v73
	v_lshlrev_b32_e32 v216, 16, v74
	v_and_b32_e32 v217, s44, v74
	v_lshlrev_b32_e32 v222, 16, v75
	v_and_b32_e32 v223, s44, v75
	v_pk_add_f32 v[204:205], v[204:205], v[212:213]
	v_pk_add_f32 v[206:207], v[206:207], v[214:215]
	v_pk_add_f32 v[208:209], v[208:209], v[216:217]
	v_pk_add_f32 v[210:211], v[210:211], v[222:223]
	s_waitcnt vmcnt(16)
	v_cvt_pk_bf16_f32 v80, v80, v81
	v_cvt_pk_bf16_f32 v81, v82, v83
	v_cvt_pk_bf16_f32 v82, v84, v85
	v_cvt_pk_bf16_f32 v83, v86, v87
	v_lshlrev_b32_e32 v212, 16, v80
	v_and_b32_e32 v213, s44, v80
	v_lshlrev_b32_e32 v214, 16, v81
	v_and_b32_e32 v215, s44, v81
	v_lshlrev_b32_e32 v216, 16, v82
	v_and_b32_e32 v217, s44, v82
	v_lshlrev_b32_e32 v222, 16, v83
	v_and_b32_e32 v223, s44, v83
	v_pk_add_f32 v[204:205], v[204:205], v[212:213]
	v_pk_add_f32 v[206:207], v[206:207], v[214:215]
	v_pk_add_f32 v[208:209], v[208:209], v[216:217]
	v_pk_add_f32 v[210:211], v[210:211], v[222:223]
	s_waitcnt vmcnt(14)
	v_cvt_pk_bf16_f32 v88, v88, v89
	v_cvt_pk_bf16_f32 v89, v90, v91
	v_cvt_pk_bf16_f32 v90, v92, v93
	v_cvt_pk_bf16_f32 v91, v94, v95
	v_lshlrev_b32_e32 v212, 16, v88
	v_and_b32_e32 v213, s44, v88
	v_lshlrev_b32_e32 v214, 16, v89
	v_and_b32_e32 v215, s44, v89
	v_lshlrev_b32_e32 v216, 16, v90
	v_and_b32_e32 v217, s44, v90
	v_lshlrev_b32_e32 v222, 16, v91
	v_and_b32_e32 v223, s44, v91
	v_pk_add_f32 v[204:205], v[204:205], v[212:213]
	v_pk_add_f32 v[206:207], v[206:207], v[214:215]
	v_pk_add_f32 v[208:209], v[208:209], v[216:217]
	v_pk_add_f32 v[210:211], v[210:211], v[222:223]
	s_waitcnt vmcnt(12)
	v_cvt_pk_bf16_f32 v96, v96, v97
	v_cvt_pk_bf16_f32 v97, v98, v99
	v_cvt_pk_bf16_f32 v98, v100, v101
	v_cvt_pk_bf16_f32 v99, v102, v103
	v_lshlrev_b32_e32 v212, 16, v96
	v_and_b32_e32 v213, s44, v96
	v_lshlrev_b32_e32 v214, 16, v97
	v_and_b32_e32 v215, s44, v97
	v_lshlrev_b32_e32 v216, 16, v98
	v_and_b32_e32 v217, s44, v98
	v_lshlrev_b32_e32 v222, 16, v99
	v_and_b32_e32 v223, s44, v99
	v_pk_add_f32 v[204:205], v[204:205], v[212:213]
	v_pk_add_f32 v[206:207], v[206:207], v[214:215]
	v_pk_add_f32 v[208:209], v[208:209], v[216:217]
	v_pk_add_f32 v[210:211], v[210:211], v[222:223]
	s_waitcnt vmcnt(10)
	v_cvt_pk_bf16_f32 v104, v104, v105
	v_cvt_pk_bf16_f32 v105, v106, v107
	v_cvt_pk_bf16_f32 v106, v108, v109
	v_cvt_pk_bf16_f32 v107, v110, v111
	v_lshlrev_b32_e32 v212, 16, v104
	v_and_b32_e32 v213, s44, v104
	v_lshlrev_b32_e32 v214, 16, v105
	v_and_b32_e32 v215, s44, v105
	v_lshlrev_b32_e32 v216, 16, v106
	v_and_b32_e32 v217, s44, v106
	v_lshlrev_b32_e32 v222, 16, v107
	v_and_b32_e32 v223, s44, v107
	v_pk_add_f32 v[204:205], v[204:205], v[212:213]
	v_pk_add_f32 v[206:207], v[206:207], v[214:215]
	v_pk_add_f32 v[208:209], v[208:209], v[216:217]
	v_pk_add_f32 v[210:211], v[210:211], v[222:223]
	s_waitcnt vmcnt(8)
	v_cvt_pk_bf16_f32 v112, v112, v113
	v_cvt_pk_bf16_f32 v113, v114, v115
	v_cvt_pk_bf16_f32 v114, v116, v117
	v_cvt_pk_bf16_f32 v115, v118, v119
	v_lshlrev_b32_e32 v212, 16, v112
	v_and_b32_e32 v213, s44, v112
	v_lshlrev_b32_e32 v214, 16, v113
	v_and_b32_e32 v215, s44, v113
	v_lshlrev_b32_e32 v216, 16, v114
	v_and_b32_e32 v217, s44, v114
	v_lshlrev_b32_e32 v222, 16, v115
	v_and_b32_e32 v223, s44, v115
	v_pk_add_f32 v[204:205], v[204:205], v[212:213]
	v_pk_add_f32 v[206:207], v[206:207], v[214:215]
	v_pk_add_f32 v[208:209], v[208:209], v[216:217]
	v_pk_add_f32 v[210:211], v[210:211], v[222:223]
	s_waitcnt vmcnt(7)
	v_lshlrev_b32_e32 v212, 16, v172
	v_and_b32_e32 v213, s44, v172
	v_lshlrev_b32_e32 v214, 16, v173
	v_and_b32_e32 v215, s44, v173
	v_lshlrev_b32_e32 v216, 16, v174
	v_and_b32_e32 v217, s44, v174
	v_lshlrev_b32_e32 v222, 16, v175
	v_and_b32_e32 v223, s44, v175
	v_pk_add_f32 v[204:205], v[204:205], v[212:213]
	v_pk_add_f32 v[206:207], v[206:207], v[214:215]
	v_pk_add_f32 v[208:209], v[208:209], v[216:217]
	v_pk_add_f32 v[210:211], v[210:211], v[222:223]
	v_fma_f32 v224, v204, s45, -v212
	v_fma_f32 v225, v205, s45, -v213
	v_cvt_pk_bf16_f32 v152, v224, v225
	v_fma_f32 v224, v206, s45, -v214
	v_fma_f32 v225, v207, s45, -v215
	v_cvt_pk_bf16_f32 v153, v224, v225
	v_fma_f32 v224, v208, s45, -v216
	v_fma_f32 v225, v209, s45, -v217
	v_cvt_pk_bf16_f32 v154, v224, v225
	v_fma_f32 v224, v210, s45, -v222
	v_fma_f32 v225, v211, s45, -v223
	v_cvt_pk_bf16_f32 v155, v224, v225
	ds_write_b128 v160, v[152:155]
	v_lshlrev_b32_e32 v212, 16, v64
	v_and_b32_e32 v213, s44, v64
	v_lshlrev_b32_e32 v214, 16, v65
	v_and_b32_e32 v215, s44, v65
	v_lshlrev_b32_e32 v216, 16, v66
	v_and_b32_e32 v217, s44, v66
	v_lshlrev_b32_e32 v222, 16, v67
	v_and_b32_e32 v223, s44, v67
	v_pk_add_f32 v[204:205], v[204:205], v[212:213] neg_lo:[0,1] neg_hi:[0,1]
	v_pk_add_f32 v[206:207], v[206:207], v[214:215] neg_lo:[0,1] neg_hi:[0,1]
	v_pk_add_f32 v[208:209], v[208:209], v[216:217] neg_lo:[0,1] neg_hi:[0,1]
	v_pk_add_f32 v[210:211], v[210:211], v[222:223] neg_lo:[0,1] neg_hi:[0,1]
	s_waitcnt vmcnt(6)
	v_lshlrev_b32_e32 v212, 16, v176
	v_and_b32_e32 v213, s44, v176
	v_lshlrev_b32_e32 v214, 16, v177
	v_and_b32_e32 v215, s44, v177
	v_lshlrev_b32_e32 v216, 16, v178
	v_and_b32_e32 v217, s44, v178
	v_lshlrev_b32_e32 v222, 16, v179
	v_and_b32_e32 v223, s44, v179
	v_pk_add_f32 v[204:205], v[204:205], v[212:213]
	v_pk_add_f32 v[206:207], v[206:207], v[214:215]
	v_pk_add_f32 v[208:209], v[208:209], v[216:217]
	v_pk_add_f32 v[210:211], v[210:211], v[222:223]
	v_fma_f32 v224, v204, s45, -v212
	v_fma_f32 v225, v205, s45, -v213
	v_cvt_pk_bf16_f32 v152, v224, v225
	v_fma_f32 v224, v206, s45, -v214
	v_fma_f32 v225, v207, s45, -v215
	v_cvt_pk_bf16_f32 v153, v224, v225
	v_fma_f32 v224, v208, s45, -v216
	v_fma_f32 v225, v209, s45, -v217
	v_cvt_pk_bf16_f32 v154, v224, v225
	v_fma_f32 v224, v210, s45, -v222
	v_fma_f32 v225, v211, s45, -v223
	v_cvt_pk_bf16_f32 v155, v224, v225
	ds_write_b128 v160, v[152:155] offset:528
	v_lshlrev_b32_e32 v212, 16, v72
	v_and_b32_e32 v213, s44, v72
	v_lshlrev_b32_e32 v214, 16, v73
	v_and_b32_e32 v215, s44, v73
	v_lshlrev_b32_e32 v216, 16, v74
	v_and_b32_e32 v217, s44, v74
	v_lshlrev_b32_e32 v222, 16, v75
	v_and_b32_e32 v223, s44, v75
	v_pk_add_f32 v[204:205], v[204:205], v[212:213] neg_lo:[0,1] neg_hi:[0,1]
	v_pk_add_f32 v[206:207], v[206:207], v[214:215] neg_lo:[0,1] neg_hi:[0,1]
	v_pk_add_f32 v[208:209], v[208:209], v[216:217] neg_lo:[0,1] neg_hi:[0,1]
	v_pk_add_f32 v[210:211], v[210:211], v[222:223] neg_lo:[0,1] neg_hi:[0,1]
	s_waitcnt vmcnt(5)
	v_lshlrev_b32_e32 v212, 16, v180
	v_and_b32_e32 v213, s44, v180
	v_lshlrev_b32_e32 v214, 16, v181
	v_and_b32_e32 v215, s44, v181
	v_lshlrev_b32_e32 v216, 16, v182
	v_and_b32_e32 v217, s44, v182
	v_lshlrev_b32_e32 v222, 16, v183
	v_and_b32_e32 v223, s44, v183
	v_pk_add_f32 v[204:205], v[204:205], v[212:213]
	v_pk_add_f32 v[206:207], v[206:207], v[214:215]
	v_pk_add_f32 v[208:209], v[208:209], v[216:217]
	v_pk_add_f32 v[210:211], v[210:211], v[222:223]
	v_fma_f32 v224, v204, s45, -v212
	v_fma_f32 v225, v205, s45, -v213
	v_cvt_pk_bf16_f32 v152, v224, v225
	v_fma_f32 v224, v206, s45, -v214
	v_fma_f32 v225, v207, s45, -v215
	v_cvt_pk_bf16_f32 v153, v224, v225
	v_fma_f32 v224, v208, s45, -v216
	v_fma_f32 v225, v209, s45, -v217
	v_cvt_pk_bf16_f32 v154, v224, v225
	v_fma_f32 v224, v210, s45, -v222
	v_fma_f32 v225, v211, s45, -v223
	v_cvt_pk_bf16_f32 v155, v224, v225
	ds_write_b128 v160, v[152:155] offset:1056
	v_lshlrev_b32_e32 v212, 16, v80
	v_and_b32_e32 v213, s44, v80
	v_lshlrev_b32_e32 v214, 16, v81
	v_and_b32_e32 v215, s44, v81
	v_lshlrev_b32_e32 v216, 16, v82
	v_and_b32_e32 v217, s44, v82
	v_lshlrev_b32_e32 v222, 16, v83
	v_and_b32_e32 v223, s44, v83
	v_pk_add_f32 v[204:205], v[204:205], v[212:213] neg_lo:[0,1] neg_hi:[0,1]
	v_pk_add_f32 v[206:207], v[206:207], v[214:215] neg_lo:[0,1] neg_hi:[0,1]
	v_pk_add_f32 v[208:209], v[208:209], v[216:217] neg_lo:[0,1] neg_hi:[0,1]
	v_pk_add_f32 v[210:211], v[210:211], v[222:223] neg_lo:[0,1] neg_hi:[0,1]
	s_waitcnt vmcnt(4)
	v_lshlrev_b32_e32 v212, 16, v184
	v_and_b32_e32 v213, s44, v184
	v_lshlrev_b32_e32 v214, 16, v185
	v_and_b32_e32 v215, s44, v185
	v_lshlrev_b32_e32 v216, 16, v186
	v_and_b32_e32 v217, s44, v186
	v_lshlrev_b32_e32 v222, 16, v187
	v_and_b32_e32 v223, s44, v187
	v_pk_add_f32 v[204:205], v[204:205], v[212:213]
	v_pk_add_f32 v[206:207], v[206:207], v[214:215]
	v_pk_add_f32 v[208:209], v[208:209], v[216:217]
	v_pk_add_f32 v[210:211], v[210:211], v[222:223]
	v_fma_f32 v224, v204, s45, -v212
	v_fma_f32 v225, v205, s45, -v213
	v_cvt_pk_bf16_f32 v152, v224, v225
	v_fma_f32 v224, v206, s45, -v214
	v_fma_f32 v225, v207, s45, -v215
	v_cvt_pk_bf16_f32 v153, v224, v225
	v_fma_f32 v224, v208, s45, -v216
	v_fma_f32 v225, v209, s45, -v217
	v_cvt_pk_bf16_f32 v154, v224, v225
	v_fma_f32 v224, v210, s45, -v222
	v_fma_f32 v225, v211, s45, -v223
	v_cvt_pk_bf16_f32 v155, v224, v225
	ds_write_b128 v160, v[152:155] offset:1584
	v_lshlrev_b32_e32 v212, 16, v88
	v_and_b32_e32 v213, s44, v88
	v_lshlrev_b32_e32 v214, 16, v89
	v_and_b32_e32 v215, s44, v89
	v_lshlrev_b32_e32 v216, 16, v90
	v_and_b32_e32 v217, s44, v90
	v_lshlrev_b32_e32 v222, 16, v91
	v_and_b32_e32 v223, s44, v91
	v_pk_add_f32 v[204:205], v[204:205], v[212:213] neg_lo:[0,1] neg_hi:[0,1]
	v_pk_add_f32 v[206:207], v[206:207], v[214:215] neg_lo:[0,1] neg_hi:[0,1]
	v_pk_add_f32 v[208:209], v[208:209], v[216:217] neg_lo:[0,1] neg_hi:[0,1]
	v_pk_add_f32 v[210:211], v[210:211], v[222:223] neg_lo:[0,1] neg_hi:[0,1]
	s_waitcnt vmcnt(3)
	v_lshlrev_b32_e32 v212, 16, v188
	v_and_b32_e32 v213, s44, v188
	v_lshlrev_b32_e32 v214, 16, v189
	v_and_b32_e32 v215, s44, v189
	v_lshlrev_b32_e32 v216, 16, v190
	v_and_b32_e32 v217, s44, v190
	v_lshlrev_b32_e32 v222, 16, v191
	v_and_b32_e32 v223, s44, v191
	v_pk_add_f32 v[204:205], v[204:205], v[212:213]
	v_pk_add_f32 v[206:207], v[206:207], v[214:215]
	v_pk_add_f32 v[208:209], v[208:209], v[216:217]
	v_pk_add_f32 v[210:211], v[210:211], v[222:223]
	v_fma_f32 v224, v204, s45, -v212
	v_fma_f32 v225, v205, s45, -v213
	v_cvt_pk_bf16_f32 v152, v224, v225
	v_fma_f32 v224, v206, s45, -v214
	v_fma_f32 v225, v207, s45, -v215
	v_cvt_pk_bf16_f32 v153, v224, v225
	v_fma_f32 v224, v208, s45, -v216
	v_fma_f32 v225, v209, s45, -v217
	v_cvt_pk_bf16_f32 v154, v224, v225
	v_fma_f32 v224, v210, s45, -v222
	v_fma_f32 v225, v211, s45, -v223
	v_cvt_pk_bf16_f32 v155, v224, v225
	ds_write_b128 v160, v[152:155] offset:2112
	v_lshlrev_b32_e32 v212, 16, v96
	v_and_b32_e32 v213, s44, v96
	v_lshlrev_b32_e32 v214, 16, v97
	v_and_b32_e32 v215, s44, v97
	v_lshlrev_b32_e32 v216, 16, v98
	v_and_b32_e32 v217, s44, v98
	v_lshlrev_b32_e32 v222, 16, v99
	v_and_b32_e32 v223, s44, v99
	v_pk_add_f32 v[204:205], v[204:205], v[212:213] neg_lo:[0,1] neg_hi:[0,1]
	v_pk_add_f32 v[206:207], v[206:207], v[214:215] neg_lo:[0,1] neg_hi:[0,1]
	v_pk_add_f32 v[208:209], v[208:209], v[216:217] neg_lo:[0,1] neg_hi:[0,1]
	v_pk_add_f32 v[210:211], v[210:211], v[222:223] neg_lo:[0,1] neg_hi:[0,1]
	s_waitcnt vmcnt(2)
	v_lshlrev_b32_e32 v212, 16, v192
	v_and_b32_e32 v213, s44, v192
	v_lshlrev_b32_e32 v214, 16, v193
	v_and_b32_e32 v215, s44, v193
	v_lshlrev_b32_e32 v216, 16, v194
	v_and_b32_e32 v217, s44, v194
	v_lshlrev_b32_e32 v222, 16, v195
	v_and_b32_e32 v223, s44, v195
	v_pk_add_f32 v[204:205], v[204:205], v[212:213]
	v_pk_add_f32 v[206:207], v[206:207], v[214:215]
	v_pk_add_f32 v[208:209], v[208:209], v[216:217]
	v_pk_add_f32 v[210:211], v[210:211], v[222:223]
	v_fma_f32 v224, v204, s45, -v212
	v_fma_f32 v225, v205, s45, -v213
	v_cvt_pk_bf16_f32 v152, v224, v225
	v_fma_f32 v224, v206, s45, -v214
	v_fma_f32 v225, v207, s45, -v215
	v_cvt_pk_bf16_f32 v153, v224, v225
	v_fma_f32 v224, v208, s45, -v216
	v_fma_f32 v225, v209, s45, -v217
	v_cvt_pk_bf16_f32 v154, v224, v225
	v_fma_f32 v224, v210, s45, -v222
	v_fma_f32 v225, v211, s45, -v223
	v_cvt_pk_bf16_f32 v155, v224, v225
	ds_write_b128 v160, v[152:155] offset:2640
	v_lshlrev_b32_e32 v212, 16, v104
	v_and_b32_e32 v213, s44, v104
	v_lshlrev_b32_e32 v214, 16, v105
	v_and_b32_e32 v215, s44, v105
	v_lshlrev_b32_e32 v216, 16, v106
	v_and_b32_e32 v217, s44, v106
	v_lshlrev_b32_e32 v222, 16, v107
	v_and_b32_e32 v223, s44, v107
	v_pk_add_f32 v[204:205], v[204:205], v[212:213] neg_lo:[0,1] neg_hi:[0,1]
	v_pk_add_f32 v[206:207], v[206:207], v[214:215] neg_lo:[0,1] neg_hi:[0,1]
	v_pk_add_f32 v[208:209], v[208:209], v[216:217] neg_lo:[0,1] neg_hi:[0,1]
	v_pk_add_f32 v[210:211], v[210:211], v[222:223] neg_lo:[0,1] neg_hi:[0,1]
	s_waitcnt vmcnt(1)
	v_lshlrev_b32_e32 v212, 16, v196
	v_and_b32_e32 v213, s44, v196
	v_lshlrev_b32_e32 v214, 16, v197
	v_and_b32_e32 v215, s44, v197
	v_lshlrev_b32_e32 v216, 16, v198
	v_and_b32_e32 v217, s44, v198
	v_lshlrev_b32_e32 v222, 16, v199
	v_and_b32_e32 v223, s44, v199
	v_pk_add_f32 v[204:205], v[204:205], v[212:213]
	v_pk_add_f32 v[206:207], v[206:207], v[214:215]
	v_pk_add_f32 v[208:209], v[208:209], v[216:217]
	v_pk_add_f32 v[210:211], v[210:211], v[222:223]
	v_fma_f32 v224, v204, s45, -v212
	v_fma_f32 v225, v205, s45, -v213
	v_cvt_pk_bf16_f32 v152, v224, v225
	v_fma_f32 v224, v206, s45, -v214
	v_fma_f32 v225, v207, s45, -v215
	v_cvt_pk_bf16_f32 v153, v224, v225
	v_fma_f32 v224, v208, s45, -v216
	v_fma_f32 v225, v209, s45, -v217
	v_cvt_pk_bf16_f32 v154, v224, v225
	v_fma_f32 v224, v210, s45, -v222
	v_fma_f32 v225, v211, s45, -v223
	v_cvt_pk_bf16_f32 v155, v224, v225
	ds_write_b128 v160, v[152:155] offset:3168
	v_lshlrev_b32_e32 v212, 16, v112
	v_and_b32_e32 v213, s44, v112
	v_lshlrev_b32_e32 v214, 16, v113
	v_and_b32_e32 v215, s44, v113
	v_lshlrev_b32_e32 v216, 16, v114
	v_and_b32_e32 v217, s44, v114
	v_lshlrev_b32_e32 v222, 16, v115
	v_and_b32_e32 v223, s44, v115
	v_pk_add_f32 v[204:205], v[204:205], v[212:213] neg_lo:[0,1] neg_hi:[0,1]
	v_pk_add_f32 v[206:207], v[206:207], v[214:215] neg_lo:[0,1] neg_hi:[0,1]
	v_pk_add_f32 v[208:209], v[208:209], v[216:217] neg_lo:[0,1] neg_hi:[0,1]
	v_pk_add_f32 v[210:211], v[210:211], v[222:223] neg_lo:[0,1] neg_hi:[0,1]
	s_waitcnt vmcnt(0)
	v_lshlrev_b32_e32 v212, 16, v200
	v_and_b32_e32 v213, s44, v200
	v_lshlrev_b32_e32 v214, 16, v201
	v_and_b32_e32 v215, s44, v201
	v_lshlrev_b32_e32 v216, 16, v202
	v_and_b32_e32 v217, s44, v202
	v_lshlrev_b32_e32 v222, 16, v203
	v_and_b32_e32 v223, s44, v203
	v_pk_add_f32 v[204:205], v[204:205], v[212:213]
	v_pk_add_f32 v[206:207], v[206:207], v[214:215]
	v_pk_add_f32 v[208:209], v[208:209], v[216:217]
	v_pk_add_f32 v[210:211], v[210:211], v[222:223]
	v_fma_f32 v224, v204, s45, -v212
	v_fma_f32 v225, v205, s45, -v213
	v_cvt_pk_bf16_f32 v64, v224, v225
	v_fma_f32 v224, v206, s45, -v214
	v_fma_f32 v225, v207, s45, -v215
	v_cvt_pk_bf16_f32 v65, v224, v225
	v_fma_f32 v224, v208, s45, -v216
	v_fma_f32 v225, v209, s45, -v217
	v_cvt_pk_bf16_f32 v66, v224, v225
	v_fma_f32 v224, v210, s45, -v222
	v_fma_f32 v225, v211, s45, -v223
	v_cvt_pk_bf16_f32 v67, v224, v225
	v_mov_b32_e32 v96, v160
	s_mov_b64 s[16:17], 0

	.amdhsa_kernel _Z9hymba_fwd6Params
		.amdhsa_group_segment_fixed_size 0
		.amdhsa_private_segment_fixed_size 0
		.amdhsa_kernarg_size 416
		.amdhsa_user_sgpr_count 2
		.amdhsa_user_sgpr_dispatch_ptr 0
		.amdhsa_user_sgpr_queue_ptr 0
		.amdhsa_user_sgpr_kernarg_segment_ptr 1
		.amdhsa_user_sgpr_dispatch_id 0
		.amdhsa_user_sgpr_kernarg_preload_length 0
		.amdhsa_user_sgpr_kernarg_preload_offset 0
		.amdhsa_user_sgpr_private_segment_size 0
		.amdhsa_uses_dynamic_stack 0
		.amdhsa_enable_private_segment 0
		.amdhsa_system_sgpr_workgroup_id_x 1
		.amdhsa_system_sgpr_workgroup_id_y 0
		.amdhsa_system_sgpr_workgroup_id_z 0
		.amdhsa_system_sgpr_workgroup_info 0
		.amdhsa_system_vgpr_workitem_id 2
		.amdhsa_next_free_vgpr 256
		.amdhsa_next_free_sgpr 102
		.amdhsa_accum_offset 256
		.amdhsa_reserve_vcc 1
		.amdhsa_float_round_mode_32 0
		.amdhsa_float_round_mode_16_64 0
		.amdhsa_float_denorm_mode_32 3
		.amdhsa_float_denorm_mode_16_64 3
		.amdhsa_dx10_clamp 1
		.amdhsa_ieee_mode 1
		.amdhsa_fp16_overflow 0
		.amdhsa_tg_split 0
		.amdhsa_exception_fp_ieee_invalid_op 0
		.amdhsa_exception_fp_denorm_src 0
		.amdhsa_exception_fp_ieee_div_zero 0
		.amdhsa_exception_fp_ieee_overflow 0
		.amdhsa_exception_fp_ieee_underflow 0
		.amdhsa_exception_fp_ieee_inexact 0
		.amdhsa_exception_int_div_zero 0
	.end_amdhsa_kernel

amdhsa.kernels:
  - .agpr_count:     0
    .args:
      - .offset:         0
        .size:           160
        .value_kind:     by_value
      - .offset:         160
        .size:           4
        .value_kind:     hidden_block_count_x
      - .offset:         164
        .size:           4
        .value_kind:     hidden_block_count_y
      - .offset:         168
        .size:           4
        .value_kind:     hidden_block_count_z
      - .offset:         172
        .size:           2
        .value_kind:     hidden_group_size_x
      - .offset:         174
        .size:           2
        .value_kind:     hidden_group_size_y
      - .offset:         176
        .size:           2
        .value_kind:     hidden_group_size_z
      - .offset:         178
        .size:           2
        .value_kind:     hidden_remainder_x
      - .offset:         180
        .size:           2
        .value_kind:     hidden_remainder_y
      - .offset:         182
        .size:           2
        .value_kind:     hidden_remainder_z
      - .offset:         200
        .size:           8
        .value_kind:     hidden_global_offset_x
      - .offset:         208
        .size:           8
        .value_kind:     hidden_global_offset_y
      - .offset:         216
        .size:           8
        .value_kind:     hidden_global_offset_z
      - .offset:         224
        .size:           2
        .value_kind:     hidden_grid_dims
      - .offset:         248
        .size:           8
        .value_kind:     hidden_multigrid_sync_arg
      - .offset:         280
        .size:           4
        .value_kind:     hidden_dynamic_lds_size
    .group_segment_fixed_size: 0
    .kernarg_segment_align: 8
    .kernarg_segment_size: 416
    .language:       OpenCL C
    .language_version:
      - 2
      - 0
    .max_flat_workgroup_size: 512
    .name:           _Z9hymba_fwd6Params
    .private_segment_fixed_size: 0
    .sgpr_count:     108
    .sgpr_spill_count: 231
    .symbol:         _Z9hymba_fwd6Params.kd
    .uniform_work_group_size: 1
    .uses_dynamic_stack: false
    .vgpr_count:     256
    .vgpr_spill_count: 0
    .wavefront_size: 64
